# E31 full grid barrier hop-skip: last XCD leader releases all XCD generation words directly, other leaders add 0
# speedup vs baseline: 1.0010x; 1.0010x over previous
; __device__ __forceinline__ unsigned xb_add(unsigned* p, unsigned v) { return __hip_atomic_fetch_add(p, v, __ATOMIC_RELAXED, __HIP_MEMORY_SCOPE_AGENT); }
; __device__ __forceinline__ void xcd_barrier(const XcdBarrier& b) {
;     ...
;         __builtin_amdgcn_s_waitcnt(0);
;         unsigned nloc = b.st[0], nx = b.st[1];
;         if (nloc == 0u) { xcd_barrier_complete(bar, bx, nloc, nx); b.st[0] = nloc; b.st[1] = nx; }
;         const unsigned old = xb_add(&bar[XB_XSUB(bx)], 1u);
;         const unsigned gen = old / nloc;
;         if (old + 1u == (gen + 1u) * nloc) {
;             __builtin_amdgcn_fence(__ATOMIC_RELEASE, "agent");
;             asm volatile("s_waitcnt vmcnt(0)" ::: "memory");
;             const unsigned og = xb_add(&bar[XB_TOP], 1u);
.LBB0_119:
	s_andn2_saveexec_b64 s[4:5], s[4:5]
	s_cbranch_execz .LBB0_139
	s_mov_b64 s[4:5], exec
	s_mov_b32 s101, 0
	buffer_wbl2 sc1
	s_waitcnt lgkmcnt(0)
	s_waitcnt vmcnt(0)
	v_mbcnt_lo_u32_b32 v1, s4, 0
	v_mbcnt_hi_u32_b32 v1, s5, v1
	v_cmp_eq_u32_e32 vcc, 0, v1
	s_and_saveexec_b64 s[6:7], vcc
	s_cbranch_execz .LBB0_122
	s_bcnt1_i32_b64 s4, s[4:5]
	v_mov_b32_e32 v2, 0xc3000
	v_mov_b32_e32 v3, s4
	global_atomic_add v2, v2, v3, s[2:3] offset:1024 sc0

; __device__ __forceinline__ unsigned xb_ld(unsigned* p)              { return __hip_atomic_load(p, __ATOMIC_RELAXED, __HIP_MEMORY_SCOPE_AGENT); }
; __device__ __forceinline__ unsigned xb_add(unsigned* p, unsigned v) { return __hip_atomic_fetch_add(p, v, __ATOMIC_RELAXED, __HIP_MEMORY_SCOPE_AGENT); }
; #define XB_SPIN(cond, bar) do { unsigned _sp = 0; while (cond) { __builtin_amdgcn_s_sleep(1); \
;     if ((++_sp & 255u) == 0u) { if (xb_ld(&(bar)[XB_TMO])) break; if (_sp > XB_SPIN_CAP) { atomicAdd(&(bar)[XB_TMO], 1u); break; } } } } while (0)
; __device__ __forceinline__ void xcd_barrier(const XcdBarrier& b) {
;     ...
;             const unsigned og = xb_add(&bar[XB_TOP], 1u);
;             const unsigned tg = og / nx;
;             if (og + 1u == (tg + 1u) * nx) xb_add(&bar[XB_TOPGEN], 1u);
;             else XB_SPIN(xb_ld(&bar[XB_TOPGEN]) == tg, bar);
;             __builtin_amdgcn_fence(__ATOMIC_ACQUIRE, "agent");
;             xb_add(&bar[XB_XGEN(bx)], 1u);
;             asm volatile("s_waitcnt vmcnt(0)" ::: "memory");
.LBB0_134:
	s_or_b64 exec, exec, s[4:5]
	s_and_saveexec_b64 s[4:5], s[8:9]
	s_cbranch_execz .LBB0_136
	v_mov_b32_e32 v2, 1
	global_atomic_add v[0:1], v2, off
	v_mov_b32_e32 v3, 0
	v_readlane_b32 s8, v254, 1
	v_readlane_b32 s9, v254, 2
	s_nop 1
	s_add_u32 s8, s8, 0x2400
	s_addc_u32 s9, s9, 0
	global_atomic_add v3, v2, s[8:9]
	global_atomic_add v3, v2, s[8:9] offset:256
	global_atomic_add v3, v2, s[8:9] offset:512
	global_atomic_add v3, v2, s[8:9] offset:768
	global_atomic_add v3, v2, s[8:9] offset:1024
	global_atomic_add v3, v2, s[8:9] offset:1280
	global_atomic_add v3, v2, s[8:9] offset:1536
	global_atomic_add v3, v2, s[8:9] offset:1792
	global_atomic_add v3, v2, s[8:9] offset:2048
	global_atomic_add v3, v2, s[8:9] offset:2304
	global_atomic_add v3, v2, s[8:9] offset:2560
	global_atomic_add v3, v2, s[8:9] offset:2816
	global_atomic_add v3, v2, s[8:9] offset:3072
	global_atomic_add v3, v2, s[8:9] offset:3328
	global_atomic_add v3, v2, s[8:9] offset:3584
	global_atomic_add v3, v2, s[8:9] offset:3840
.LBB0_136:
	s_or_b64 exec, exec, s[4:5]
	s_mov_b64 s[4:5], exec
	v_mbcnt_lo_u32_b32 v0, s4, 0
	v_mbcnt_hi_u32_b32 v0, s5, v0
	s_mov_b32 s9, 0
	v_cmp_eq_u32_e32 vcc, 0, v0
	s_waitcnt vmcnt(0)
	s_and_saveexec_b64 s[6:7], vcc
	s_cbranch_execz .LBB0_138
	s_add_i32 s8, s13, 0x900
	s_lshl_b64 s[8:9], s[8:9], 2
	v_readlane_b32 s10, v254, 1
	v_readlane_b32 s11, v254, 2
	s_add_u32 s8, s10, s8
	s_addc_u32 s9, s11, s9
	s_bcnt1_i32_b64 s4, s[4:5]
	s_cmp_lg_u32 s101, 0
	s_cselect_b32 s4, s4, 0
	v_mov_b32_e32 v0, 0
	v_mov_b32_e32 v1, s4
	global_atomic_add v0, v1, s[8:9]

; __device__ __forceinline__ unsigned xb_add(unsigned* p, unsigned v) { return __hip_atomic_fetch_add(p, v, __ATOMIC_RELAXED, __HIP_MEMORY_SCOPE_AGENT); }
; __device__ __forceinline__ void xcd_barrier(const XcdBarrier& b) {
;     ...
;         __builtin_amdgcn_s_waitcnt(0);
;         unsigned nloc = b.st[0], nx = b.st[1];
;         if (nloc == 0u) { xcd_barrier_complete(bar, bx, nloc, nx); b.st[0] = nloc; b.st[1] = nx; }
;         const unsigned old = xb_add(&bar[XB_XSUB(bx)], 1u);
;         const unsigned gen = old / nloc;
;         if (old + 1u == (gen + 1u) * nloc) {
;             __builtin_amdgcn_fence(__ATOMIC_RELEASE, "agent");
;             asm volatile("s_waitcnt vmcnt(0)" ::: "memory");
;             const unsigned og = xb_add(&bar[XB_TOP], 1u);
.LBB0_302:
	s_andn2_saveexec_b64 s[2:3], s[2:3]
	s_cbranch_execz .LBB0_322
	s_mov_b64 s[2:3], exec
	s_mov_b32 s101, 0
	buffer_wbl2 sc1
	s_waitcnt lgkmcnt(0)
	s_waitcnt vmcnt(0)
	v_mbcnt_lo_u32_b32 v1, s2, 0
	v_mbcnt_hi_u32_b32 v1, s3, v1
	v_cmp_eq_u32_e32 vcc, 0, v1
	s_and_saveexec_b64 s[4:5], vcc
	s_cbranch_execz .LBB0_305
	s_bcnt1_i32_b64 s2, s[2:3]
	v_mov_b32_e32 v2, s2
	v_readlane_b32 s2, v254, 24
	v_readlane_b32 s3, v254, 25
	s_nop 4
	global_atomic_add v2, v157, v2, s[2:3] sc0

; __device__ __forceinline__ unsigned xb_ld(unsigned* p)              { return __hip_atomic_load(p, __ATOMIC_RELAXED, __HIP_MEMORY_SCOPE_AGENT); }
; __device__ __forceinline__ unsigned xb_add(unsigned* p, unsigned v) { return __hip_atomic_fetch_add(p, v, __ATOMIC_RELAXED, __HIP_MEMORY_SCOPE_AGENT); }
; #define XB_SPIN(cond, bar) do { unsigned _sp = 0; while (cond) { __builtin_amdgcn_s_sleep(1); \
;     if ((++_sp & 255u) == 0u) { if (xb_ld(&(bar)[XB_TMO])) break; if (_sp > XB_SPIN_CAP) { atomicAdd(&(bar)[XB_TMO], 1u); break; } } } } while (0)
; __device__ __forceinline__ void xcd_barrier(const XcdBarrier& b) {
;     ...
;             const unsigned og = xb_add(&bar[XB_TOP], 1u);
;             const unsigned tg = og / nx;
;             if (og + 1u == (tg + 1u) * nx) xb_add(&bar[XB_TOPGEN], 1u);
;             else XB_SPIN(xb_ld(&bar[XB_TOPGEN]) == tg, bar);
;             __builtin_amdgcn_fence(__ATOMIC_ACQUIRE, "agent");
;             xb_add(&bar[XB_XGEN(bx)], 1u);
;             asm volatile("s_waitcnt vmcnt(0)" ::: "memory");
.LBB0_317:
	s_or_b64 exec, exec, s[2:3]
	s_and_saveexec_b64 s[2:3], s[4:5]
	s_cbranch_execz .LBB0_319
	global_atomic_add v[0:1], v213, off
	v_readlane_b32 s6, v254, 1
	v_readlane_b32 s7, v254, 2
	s_nop 1
	s_add_u32 s6, s6, 0x2400
	s_addc_u32 s7, s7, 0
	global_atomic_add v157, v213, s[6:7]
	global_atomic_add v157, v213, s[6:7] offset:256
	global_atomic_add v157, v213, s[6:7] offset:512
	global_atomic_add v157, v213, s[6:7] offset:768
	global_atomic_add v157, v213, s[6:7] offset:1024
	global_atomic_add v157, v213, s[6:7] offset:1280
	global_atomic_add v157, v213, s[6:7] offset:1536
	global_atomic_add v157, v213, s[6:7] offset:1792
	global_atomic_add v157, v213, s[6:7] offset:2048
	global_atomic_add v157, v213, s[6:7] offset:2304
	global_atomic_add v157, v213, s[6:7] offset:2560
	global_atomic_add v157, v213, s[6:7] offset:2816
	global_atomic_add v157, v213, s[6:7] offset:3072
	global_atomic_add v157, v213, s[6:7] offset:3328
	global_atomic_add v157, v213, s[6:7] offset:3584
	global_atomic_add v157, v213, s[6:7] offset:3840
.LBB0_319:
	s_or_b64 exec, exec, s[2:3]
	s_mov_b64 s[2:3], exec
	v_mbcnt_lo_u32_b32 v0, s2, 0
	v_mbcnt_hi_u32_b32 v0, s3, v0
	v_cmp_eq_u32_e32 vcc, 0, v0
	s_waitcnt vmcnt(0)
	s_and_saveexec_b64 s[4:5], vcc
	s_cbranch_execz .LBB0_321
	s_add_i32 s96, s18, 0x900
	s_lshl_b64 s[6:7], s[96:97], 2
	v_readlane_b32 s8, v254, 1
	v_readlane_b32 s9, v254, 2
	s_add_u32 s6, s8, s6
	s_addc_u32 s7, s9, s7
	s_bcnt1_i32_b64 s2, s[2:3]
	s_cmp_lg_u32 s101, 0
	s_cselect_b32 s2, s2, 0
	v_mov_b32_e32 v0, s2
	global_atomic_add v157, v0, s[6:7]
	v_readlane_b32 s96, v215, 35

; __device__ __forceinline__ unsigned xb_ld(unsigned* p)              { return __hip_atomic_load(p, __ATOMIC_RELAXED, __HIP_MEMORY_SCOPE_AGENT); }
; __device__ __forceinline__ unsigned xb_add(unsigned* p, unsigned v) { return __hip_atomic_fetch_add(p, v, __ATOMIC_RELAXED, __HIP_MEMORY_SCOPE_AGENT); }
; #define XB_SPIN(cond, bar) do { unsigned _sp = 0; while (cond) { __builtin_amdgcn_s_sleep(1); \
;     if ((++_sp & 255u) == 0u) { if (xb_ld(&(bar)[XB_TMO])) break; if (_sp > XB_SPIN_CAP) { atomicAdd(&(bar)[XB_TMO], 1u); break; } } } } while (0)
; __device__ __forceinline__ void xcd_barrier(const XcdBarrier& b) {
;     ...
;             const unsigned og = xb_add(&bar[XB_TOP], 1u);
;             const unsigned tg = og / nx;
;             if (og + 1u == (tg + 1u) * nx) xb_add(&bar[XB_TOPGEN], 1u);
;             else XB_SPIN(xb_ld(&bar[XB_TOPGEN]) == tg, bar);
;             __builtin_amdgcn_fence(__ATOMIC_ACQUIRE, "agent");
;             xb_add(&bar[XB_XGEN(bx)], 1u);
;             asm volatile("s_waitcnt vmcnt(0)" ::: "memory");
.LBB0_490:
	s_or_b64 exec, exec, s[10:11]
	s_and_saveexec_b64 s[10:11], s[12:13]
	s_cbranch_execz .LBB0_492
	global_atomic_add v[0:1], v213, off
	v_readlane_b32 s14, v254, 1
	v_readlane_b32 s15, v254, 2
	s_nop 1
	s_add_u32 s14, s14, 0x2400
	s_addc_u32 s15, s15, 0
	global_atomic_add v157, v213, s[14:15]
	global_atomic_add v157, v213, s[14:15] offset:256
	global_atomic_add v157, v213, s[14:15] offset:512
	global_atomic_add v157, v213, s[14:15] offset:768
	global_atomic_add v157, v213, s[14:15] offset:1024
	global_atomic_add v157, v213, s[14:15] offset:1280
	global_atomic_add v157, v213, s[14:15] offset:1536
	global_atomic_add v157, v213, s[14:15] offset:1792
	global_atomic_add v157, v213, s[14:15] offset:2048
	global_atomic_add v157, v213, s[14:15] offset:2304
	global_atomic_add v157, v213, s[14:15] offset:2560
	global_atomic_add v157, v213, s[14:15] offset:2816
	global_atomic_add v157, v213, s[14:15] offset:3072
	global_atomic_add v157, v213, s[14:15] offset:3328
	global_atomic_add v157, v213, s[14:15] offset:3584
	global_atomic_add v157, v213, s[14:15] offset:3840
.LBB0_492:
	s_or_b64 exec, exec, s[10:11]
	s_mov_b64 s[10:11], exec
	v_mbcnt_lo_u32_b32 v0, s10, 0
	v_mbcnt_hi_u32_b32 v0, s11, v0
	v_cmp_eq_u32_e32 vcc, 0, v0
	s_waitcnt vmcnt(0)
	s_and_saveexec_b64 s[12:13], vcc
	s_cbranch_execz .LBB0_494
	s_add_i32 s96, s26, 0x900
	s_lshl_b64 s[14:15], s[96:97], 2
	v_readlane_b32 s16, v254, 1
	v_readlane_b32 s17, v254, 2
	s_add_u32 s14, s16, s14
	s_addc_u32 s15, s17, s15
	s_bcnt1_i32_b64 s10, s[10:11]
	s_cmp_lg_u32 s101, 0
	s_cselect_b32 s10, s10, 0
	v_mov_b32_e32 v0, s10
	global_atomic_add v157, v0, s[14:15]
	v_readlane_b32 s96, v215, 35

; __device__ __forceinline__ unsigned xb_add(unsigned* p, unsigned v) { return __hip_atomic_fetch_add(p, v, __ATOMIC_RELAXED, __HIP_MEMORY_SCOPE_AGENT); }
; __device__ __forceinline__ void xcd_barrier(const XcdBarrier& b) {
;     ...
;         if (old + 1u == (gen + 1u) * nloc) {
;             __builtin_amdgcn_fence(__ATOMIC_RELEASE, "agent");
;             asm volatile("s_waitcnt vmcnt(0)" ::: "memory");
;             const unsigned og = xb_add(&bar[XB_TOP], 1u);
.LBB0_1513:
	s_mov_b64 s[2:3], exec
	s_mov_b32 s101, 0
	buffer_wbl2 sc1
	s_waitcnt lgkmcnt(0)
	s_waitcnt vmcnt(0)
	v_mbcnt_lo_u32_b32 v1, s2, 0
	v_mbcnt_hi_u32_b32 v1, s3, v1
	v_cmp_eq_u32_e32 vcc, 0, v1
	s_and_saveexec_b64 s[4:5], vcc
	s_cbranch_execz .LBB0_1515
	s_bcnt1_i32_b64 s2, s[2:3]
	v_mov_b32_e32 v2, s2
	v_readlane_b32 s2, v254, 24
	v_readlane_b32 s3, v254, 25
	s_nop 4
	global_atomic_add v2, v157, v2, s[2:3] sc0

; __device__ __forceinline__ unsigned xb_ld(unsigned* p)              { return __hip_atomic_load(p, __ATOMIC_RELAXED, __HIP_MEMORY_SCOPE_AGENT); }
; __device__ __forceinline__ unsigned xb_add(unsigned* p, unsigned v) { return __hip_atomic_fetch_add(p, v, __ATOMIC_RELAXED, __HIP_MEMORY_SCOPE_AGENT); }
; #define XB_SPIN(cond, bar) do { unsigned _sp = 0; while (cond) { __builtin_amdgcn_s_sleep(1); \
;     if ((++_sp & 255u) == 0u) { if (xb_ld(&(bar)[XB_TMO])) break; if (_sp > XB_SPIN_CAP) { atomicAdd(&(bar)[XB_TMO], 1u); break; } } } } while (0)
; __device__ __forceinline__ void xcd_barrier(const XcdBarrier& b) {
;     ...
;             if (og + 1u == (tg + 1u) * nx) xb_add(&bar[XB_TOPGEN], 1u);
;             else XB_SPIN(xb_ld(&bar[XB_TOPGEN]) == tg, bar);
;             __builtin_amdgcn_fence(__ATOMIC_ACQUIRE, "agent");
;             xb_add(&bar[XB_XGEN(bx)], 1u);
;             asm volatile("s_waitcnt vmcnt(0)" ::: "memory");
.LBB0_1530:
	s_add_i32 s96, s18, 0x900
	s_lshl_b64 s[6:7], s[96:97], 2
	v_readlane_b32 s8, v254, 1
	v_readlane_b32 s9, v254, 2
	s_add_u32 s6, s8, s6
	s_addc_u32 s7, s9, s7
	s_bcnt1_i32_b64 s2, s[2:3]
	s_cmp_lg_u32 s101, 0
	s_cselect_b32 s2, s2, 0
	v_mov_b32_e32 v0, s2
	global_atomic_add v157, v0, s[6:7]
	v_readlane_b32 s96, v215, 35
	s_getpc_b64 s[98:99]
